# attention loop: mask-arrival waits moved from the heads of the vector segments to the matrix-segment tails, padding nops at the segment heads dropped
# baseline (speedup 1.0000x reference)
; template <int KB>
; __device__ __forceinline__ void qkt(f32x16& p0, f32x16& p1, const char* K_lds, int r32, int hi, const bf16x8* qr) {
;     p0 = f32x16{}; p1 = f32x16{};
;     const char* kb[4];
; #pragma unroll
;     for (int dd = 0; dd < 4; ++dd) kb[dd] = K_lds + KB * SHM_K + KSWZ(r32, (dd * 16 + hi * 8) * 2);
; #pragma unroll
;     for (int d0 = 0; d0 < 8; ++d0) { const char* a = kb[d0 & 3] + (d0 >> 2) * 128;
;         bf16x8 b0 = *reinterpret_cast<const bf16x8*>(a);
;         bf16x8 b1 = *reinterpret_cast<const bf16x8*>(a + 32 * 256);
;         p0 = __builtin_amdgcn_mfma_f32_32x32x16_bf16(b0, qr[d0], p0, 0, 0, 0);
;         p1 = __builtin_amdgcn_mfma_f32_32x32x16_bf16(b1, qr[d0], p1, 0, 0, 0); }
; }
; template <int VB>
; __device__ __forceinline__ void pv_tile(f32x16* o, int vb0, bf16x8 pa0, bf16x8 pa1, bf16x8 pa2, bf16x8 pa3) {
;     ...
;     PV_D0(0); PV_D0(1); PV_D0(2); PV_D0(3);
.Lp5_vw_a:
	global_load_dwordx2 v[146:147], v179, s[68:69] offset:-8
	s_add_u32 s98, s16, 0x40000
	s_addc_u32 s99, s17, 0
	global_load_dwordx4 v[130:133], v188, s[98:99]
	s_add_u32 s98, s16, 0x50000
	s_addc_u32 s99, s17, 0
	global_load_dwordx4 v[134:137], v188, s[98:99]
	ds_read_b128 v[66:69], v199 offset:49152
	ds_read_b128 v[82:85], v199 offset:57344
	ds_read_b128 v[172:175], v200 offset:49152
	ds_read_b128 v[232:235], v200 offset:57344
	ds_read_b128 v[236:239], v201 offset:49152
	ds_read_b128 v[240:243], v201 offset:57344
	ds_read_b128 v[244:247], v202 offset:49152
	s_waitcnt lgkmcnt(6)
	v_mfma_f32_32x32x16_bf16 v[66:81], v[66:69], v[126:129], 0
	s_waitcnt lgkmcnt(5)
	v_mfma_f32_32x32x16_bf16 v[82:97], v[82:85], v[126:129], 0
	s_waitcnt lgkmcnt(4)
	v_mfma_f32_32x32x16_bf16 v[66:81], v[172:175], v[122:125], v[66:81]
	ds_read_b128 v[172:175], v202 offset:57344
	s_waitcnt lgkmcnt(4)
	v_mfma_f32_32x32x16_bf16 v[82:97], v[232:235], v[122:125], v[82:97]
	ds_read_b128 v[232:235], v199 offset:49280
	s_waitcnt lgkmcnt(4)
	v_mfma_f32_32x32x16_bf16 v[66:81], v[236:239], v[118:121], v[66:81]
	ds_read_b128 v[236:239], v199 offset:57472
	s_waitcnt lgkmcnt(4)
	v_mfma_f32_32x32x16_bf16 v[82:97], v[240:243], v[118:121], v[82:97]
	ds_read_b128 v[240:243], v200 offset:49280
	s_waitcnt lgkmcnt(4)
	v_mfma_f32_32x32x16_bf16 v[66:81], v[244:247], v[114:117], v[66:81]
	ds_read_b128 v[244:247], v200 offset:57472
	s_waitcnt lgkmcnt(4)
	v_mfma_f32_32x32x16_bf16 v[82:97], v[172:175], v[114:117], v[82:97]
	ds_read_b128 v[172:175], v201 offset:49280
	s_waitcnt lgkmcnt(4)
	v_mfma_f32_32x32x16_bf16 v[66:81], v[232:235], v[110:113], v[66:81]
	ds_read_b128 v[232:235], v201 offset:57472
	s_waitcnt lgkmcnt(4)
	v_mfma_f32_32x32x16_bf16 v[82:97], v[236:239], v[110:113], v[82:97]
	ds_read_b128 v[236:239], v202 offset:49280
	s_waitcnt lgkmcnt(4)
	v_mfma_f32_32x32x16_bf16 v[66:81], v[240:243], v[106:109], v[66:81]
	ds_read_b64_tr_b16 v[212:213], v1 offset:0x0
	ds_read_b64_tr_b16 v[214:215], v1 offset:0x800
	ds_read_b64_tr_b16 v[216:217], v1 offset:0x200
	ds_read_b64_tr_b16 v[218:219], v1 offset:0xa00
	ds_read_b64_tr_b16 v[220:221], v1 offset:0x400
	ds_read_b64_tr_b16 v[222:223], v1 offset:0xc00
	ds_read_b64_tr_b16 v[224:225], v1 offset:0x600
	ds_read_b64_tr_b16 v[226:227], v1 offset:0xe00
	ds_read_b128 v[240:243], v202 offset:57472
	s_waitcnt lgkmcnt(12)
	v_mfma_f32_32x32x16_bf16 v[82:97], v[244:247], v[106:109], v[82:97]
	s_waitcnt lgkmcnt(11)
	v_mfma_f32_32x32x16_bf16 v[66:81], v[172:175], v[102:105], v[66:81]
	s_waitcnt lgkmcnt(10)
	v_mfma_f32_32x32x16_bf16 v[82:97], v[232:235], v[102:105], v[82:97]
	s_waitcnt lgkmcnt(9)
	v_mfma_f32_32x32x16_bf16 v[66:81], v[236:239], v[98:101], v[66:81]
	s_waitcnt lgkmcnt(0)
	v_mfma_f32_32x32x16_bf16 v[82:97], v[240:243], v[98:101], v[82:97]
	ds_read_b64_tr_b16 v[248:249], v1 offset:0x1000
	ds_read_b64_tr_b16 v[250:251], v1 offset:0x1800
	ds_read_b64_tr_b16 v[172:173], v1 offset:0x1200
	ds_read_b64_tr_b16 v[174:175], v1 offset:0x1a00
	ds_read_b64_tr_b16 v[232:233], v1 offset:0x1400
	ds_read_b64_tr_b16 v[234:235], v1 offset:0x1c00
	s_waitcnt lgkmcnt(13)
	v_mfma_f32_32x32x16_bf16 v[2:17], v[148:151], v[212:215], v[2:17]
	ds_read_b64_tr_b16 v[236:237], v1 offset:0x1600
	ds_read_b64_tr_b16 v[238:239], v1 offset:0x1e00
	s_waitcnt lgkmcnt(13)
	v_mfma_f32_32x32x16_bf16 v[50:65], v[148:151], v[216:219], v[50:65]
	ds_read_b64_tr_b16 v[240:241], v1 offset:0x2000
	ds_read_b64_tr_b16 v[242:243], v1 offset:0x2800
	s_waitcnt lgkmcnt(13)
	v_mfma_f32_32x32x16_bf16 v[34:49], v[148:151], v[220:223], v[34:49]
	ds_read_b64_tr_b16 v[244:245], v1 offset:0x2200
	ds_read_b64_tr_b16 v[246:247], v1 offset:0x2a00
	s_waitcnt lgkmcnt(13)
	v_mfma_f32_32x32x16_bf16 v[18:33], v[148:151], v[224:227], v[18:33]
	ds_read_b64_tr_b16 v[224:225], v1 offset:0x2400
	ds_read_b64_tr_b16 v[226:227], v1 offset:0x2c00
	s_waitcnt lgkmcnt(12)
	v_mfma_f32_32x32x16_bf16 v[2:17], v[152:155], v[248:251], v[2:17]
	ds_read_b64_tr_b16 v[248:249], v1 offset:0x2600
	ds_read_b64_tr_b16 v[250:251], v1 offset:0x2e00
	s_waitcnt lgkmcnt(12)
	v_mfma_f32_32x32x16_bf16 v[50:65], v[152:155], v[172:175], v[50:65]
	ds_read_b64_tr_b16 v[172:173], v1 offset:0x3000
	ds_read_b64_tr_b16 v[174:175], v1 offset:0x3800
	s_waitcnt lgkmcnt(12)
	v_mfma_f32_32x32x16_bf16 v[34:49], v[152:155], v[232:235], v[34:49]
	ds_read_b64_tr_b16 v[232:233], v1 offset:0x3200
	ds_read_b64_tr_b16 v[234:235], v1 offset:0x3a00
	s_waitcnt lgkmcnt(12)
	v_mfma_f32_32x32x16_bf16 v[18:33], v[152:155], v[236:239], v[18:33]
	ds_read_b64_tr_b16 v[236:237], v1 offset:0x3400
	ds_read_b64_tr_b16 v[238:239], v1 offset:0x3c00
	s_waitcnt lgkmcnt(12)
	v_mfma_f32_32x32x16_bf16 v[2:17], v[156:159], v[240:243], v[2:17]
	ds_read_b64_tr_b16 v[240:241], v1 offset:0x3600
	ds_read_b64_tr_b16 v[242:243], v1 offset:0x3e00
	s_waitcnt lgkmcnt(12)
	v_mfma_f32_32x32x16_bf16 v[50:65], v[156:159], v[244:247], v[50:65]
	s_waitcnt lgkmcnt(10)
	v_mfma_f32_32x32x16_bf16 v[34:49], v[156:159], v[224:227], v[34:49]
	s_waitcnt lgkmcnt(8)
	v_mfma_f32_32x32x16_bf16 v[18:33], v[156:159], v[248:251], v[18:33]
	s_waitcnt lgkmcnt(6)
	v_mfma_f32_32x32x16_bf16 v[2:17], v[208:211], v[172:175], v[2:17]
	s_waitcnt lgkmcnt(4)
	v_mfma_f32_32x32x16_bf16 v[50:65], v[208:211], v[232:235], v[50:65]
	s_waitcnt lgkmcnt(2)
	v_mfma_f32_32x32x16_bf16 v[34:49], v[208:211], v[236:239], v[34:49]
	s_waitcnt lgkmcnt(0)
	v_mfma_f32_32x32x16_bf16 v[18:33], v[208:211], v[240:243], v[18:33]
	s_waitcnt vmcnt(3)
	ds_write_b128 v204, v[138:141] offset:32768
	ds_write_b128 v204, v[142:145] offset:40960
	s_waitcnt vmcnt(2)
	s_add_i32 s98, s82, 2
	s_cmp_gt_u32 s98, s81
	s_cbranch_scc1 .Lp5_k2_skip
	s_add_u32 s98, s100, 0x60000
	s_addc_u32 s99, s101, 0
	global_load_dwordx4 v[138:141], v188, s[98:99]
	s_add_u32 s98, s100, 0x70000
	s_addc_u32 s99, s101, 0
	global_load_dwordx4 v[142:145], v188, s[98:99]
; __device__ __forceinline__ void sel_mask_tile(f32x16& p0, f32x16& p1, unsigned wlo, unsigned whi, int hi) {
;     const unsigned NEGB = 0xff800000u;
;     const unsigned lo = wlo >> (4 * hi), h2 = whi >> (4 * hi);
; #pragma unroll
;     for (int r = 0; r < 16; ++r) {
;         const int c = (r & 3) + 8 * (r >> 2);
;         const unsigned m0 = (unsigned)__builtin_amdgcn_sbfe((int)lo, c, 1), m1 = (unsigned)__builtin_amdgcn_sbfe((int)h2, c, 1);
;         p0[r] = __uint_as_float((__float_as_uint(p0[r]) & m0) | (NEGB & ~m0));
;         p1[r] = __uint_as_float((__float_as_uint(p1[r]) & m1) | (NEGB & ~m1));
;     }
; }
; __device__ __forceinline__ void partialSM(f32x16& p0, f32x16& p1, float& m_reg, float& mn, float& alpha) {
;     float pmax = p0[0];
; #pragma unroll
;     for (int r = 1; r < 16; ++r) pmax = fmaxf(pmax, p0[r]);
; #pragma unroll
;     for (int r = 0; r < 16; ++r) pmax = fmaxf(pmax, p1[r]);
;     { auto rr = __builtin_amdgcn_permlane32_swap(__float_as_uint(pmax), __float_as_uint(pmax), false, false);
;       pmax = fmaxf(__uint_as_float(rr[0]), __uint_as_float(rr[1])); }
;     constexpr float C2 = 1.4426950408889634f * SCALE;
;     if (__builtin_expect(__all((pmax - m_reg) * SCALE <= THR), 1)) { mn = m_reg; alpha = 1.f; }
.Lp5_k2_done:
	s_waitcnt lgkmcnt(0)
	s_barrier
	v_lshrrev_b32_e32 v160, v163, v146
	v_lshrrev_b32_e32 v161, v163, v147
	v_bfe_i32 v146, v160, 0, 1
	v_bfe_i32 v147, v161, 0, 1
	v_bitop3_b32 v146, v66, s74, v146 bitop3:0xe4
	v_bitop3_b32 v66, v82, s74, v147 bitop3:0xe4
	v_bfe_i32 v82, v160, 1, 1
	v_bfe_i32 v147, v161, 1, 1
	v_bitop3_b32 v82, v67, s74, v82 bitop3:0xe4
	v_bitop3_b32 v67, v83, s74, v147 bitop3:0xe4
	v_bfe_i32 v83, v160, 2, 1
	v_bfe_i32 v147, v161, 2, 1
	v_bitop3_b32 v83, v68, s74, v83 bitop3:0xe4
	v_bitop3_b32 v68, v84, s74, v147 bitop3:0xe4
	v_bfe_i32 v84, v160, 3, 1
	v_bfe_i32 v148, v161, 3, 1
	v_bitop3_b32 v147, v69, s74, v84 bitop3:0xe4
	v_bfe_i32 v84, v160, 8, 1
	v_bitop3_b32 v69, v85, s74, v148 bitop3:0xe4
	v_bfe_i32 v85, v161, 8, 1
	v_bitop3_b32 v148, v70, s74, v84 bitop3:0xe4
	v_bfe_i32 v84, v160, 9, 1
	v_bitop3_b32 v70, v86, s74, v85 bitop3:0xe4
	v_bfe_i32 v85, v161, 9, 1
	v_bitop3_b32 v149, v71, s74, v84 bitop3:0xe4
	v_bfe_i32 v84, v160, 10, 1
	v_bitop3_b32 v71, v87, s74, v85 bitop3:0xe4
	v_bfe_i32 v85, v161, 10, 1
	v_bitop3_b32 v87, v72, s74, v84 bitop3:0xe4
	v_bfe_i32 v84, v160, 11, 1
	v_bitop3_b32 v72, v88, s74, v85 bitop3:0xe4
	v_bfe_i32 v85, v161, 11, 1
	v_bitop3_b32 v88, v73, s74, v84 bitop3:0xe4
	v_bfe_i32 v73, v160, 16, 1
	v_bitop3_b32 v84, v89, s74, v85 bitop3:0xe4
	v_bfe_i32 v85, v161, 16, 1
	v_bitop3_b32 v89, v74, s74, v73 bitop3:0xe4
	v_bfe_i32 v73, v160, 17, 1
	v_bfe_i32 v74, v161, 17, 1
	v_bitop3_b32 v85, v90, s74, v85 bitop3:0xe4
	v_bitop3_b32 v90, v75, s74, v73 bitop3:0xe4
	v_bitop3_b32 v86, v91, s74, v74 bitop3:0xe4
	v_bfe_i32 v73, v160, 18, 1
	v_bfe_i32 v74, v161, 18, 1
	v_bitop3_b32 v91, v76, s74, v73 bitop3:0xe4
	v_bitop3_b32 v76, v92, s74, v74 bitop3:0xe4
	v_bfe_i32 v73, v160, 19, 1
	v_bfe_i32 v74, v161, 19, 1
	v_bitop3_b32 v92, v77, s74, v73 bitop3:0xe4
	v_bitop3_b32 v77, v93, s74, v74 bitop3:0xe4
	v_bfe_i32 v73, v160, 24, 1
	v_bfe_i32 v74, v161, 24, 1
	v_bitop3_b32 v93, v78, s74, v73 bitop3:0xe4
	v_bitop3_b32 v78, v94, s74, v74 bitop3:0xe4
	v_bfe_i32 v73, v160, 25, 1
	v_bfe_i32 v74, v161, 25, 1
	v_bitop3_b32 v79, v79, s74, v73 bitop3:0xe4
	v_bitop3_b32 v73, v95, s74, v74 bitop3:0xe4
	v_bfe_i32 v74, v160, 26, 1
	v_bfe_i32 v75, v161, 26, 1
	v_bitop3_b32 v80, v80, s74, v74 bitop3:0xe4
	v_bitop3_b32 v74, v96, s74, v75 bitop3:0xe4
	v_bfe_i32 v75, v160, 27, 1
	v_bfe_i32 v94, v161, 27, 1
	v_bitop3_b32 v81, v81, s74, v75 bitop3:0xe4
	v_bitop3_b32 v75, v97, s74, v94 bitop3:0xe4
	v_max_f32_e32 v94, v146, v82
	v_max3_f32 v94, v94, v83, v147
	v_max3_f32 v94, v94, v148, v149
	v_max3_f32 v94, v94, v87, v88
	v_max3_f32 v94, v94, v89, v90
	v_max3_f32 v94, v94, v91, v92
	v_max3_f32 v94, v94, v93, v79
	v_max3_f32 v94, v94, v80, v81
	v_max3_f32 v94, v94, v66, v67
	v_max3_f32 v94, v94, v68, v69
	v_max3_f32 v94, v94, v70, v71
	v_max3_f32 v94, v94, v72, v84
	v_max3_f32 v94, v94, v85, v86
	v_max3_f32 v94, v94, v76, v77
	v_max3_f32 v94, v94, v78, v73
	v_max3_f32 v94, v94, v74, v75
	v_mov_b32_e32 v95, v94
	s_nop 1
	v_permlane32_swap_b32_e32 v94, v95
	v_max_f32_e32 v94, v94, v95
	v_sub_f32_e32 v95, v94, v206
	v_mul_f32_e32 v95, 0x3db504f3, v95
	v_cmp_ge_f32_e32 vcc, s75, v95
	s_cmp_eq_u64 vcc, exec
	s_cselect_b64 s[6:7], -1, 0
	s_cbranch_scc0 .Lp5_y1_slow
	v_mov_b32_e32 v208, 1.0

; __device__ __forceinline__ void sel_mask_tile(f32x16& p0, f32x16& p1, unsigned wlo, unsigned whi, int hi) {
;     const unsigned NEGB = 0xff800000u;
;     const unsigned lo = wlo >> (4 * hi), h2 = whi >> (4 * hi);
; #pragma unroll
;     for (int r = 0; r < 16; ++r) {
;         const int c = (r & 3) + 8 * (r >> 2);
;         const unsigned m0 = (unsigned)__builtin_amdgcn_sbfe((int)lo, c, 1), m1 = (unsigned)__builtin_amdgcn_sbfe((int)h2, c, 1);
;         p0[r] = __uint_as_float((__float_as_uint(p0[r]) & m0) | (NEGB & ~m0));
;         p1[r] = __uint_as_float((__float_as_uint(p1[r]) & m1) | (NEGB & ~m1));
;     }
; }
; __device__ __forceinline__ void partialSM(f32x16& p0, f32x16& p1, float& m_reg, float& mn, float& alpha) {
;     float pmax = p0[0];
; #pragma unroll
;     for (int r = 1; r < 16; ++r) pmax = fmaxf(pmax, p0[r]);
; #pragma unroll
;     for (int r = 0; r < 16; ++r) pmax = fmaxf(pmax, p1[r]);
;     { auto rr = __builtin_amdgcn_permlane32_swap(__float_as_uint(pmax), __float_as_uint(pmax), false, false);
;       pmax = fmaxf(__uint_as_float(rr[0]), __uint_as_float(rr[1])); }
;     constexpr float C2 = 1.4426950408889634f * SCALE;
;     if (__builtin_expect(__all((pmax - m_reg) * SCALE <= THR), 1)) { mn = m_reg; alpha = 1.f; }
.Lp5_kw2_skip:
	s_waitcnt vmcnt(2)
	s_cmp_ge_u32 s82, s81
	s_cbranch_scc1 .Lp5_k1_skip
	s_add_u32 s98, s100, 0x80000
	s_addc_u32 s99, s101, 0
	global_load_dwordx4 v[138:141], v188, s[98:99]
	s_add_u32 s98, s100, 0x90000
	s_addc_u32 s99, s101, 0
	global_load_dwordx4 v[142:145], v188, s[98:99]
.Lp5_k1_skip:
	s_waitcnt lgkmcnt(0)
	s_barrier
	v_lshrrev_b32_e32 v193, v163, v228
	v_bfe_i32 v192, v193, 0, 1
	v_bitop3_b32 v192, v82, s74, v192 bitop3:0xe4
	v_bfe_i32 v82, v193, 1, 1
	v_bitop3_b32 v146, v83, s74, v82 bitop3:0xe4
	v_bfe_i32 v82, v193, 2, 1
	v_bitop3_b32 v147, v84, s74, v82 bitop3:0xe4
	v_bfe_i32 v82, v193, 3, 1
	v_bitop3_b32 v148, v85, s74, v82 bitop3:0xe4
	v_bfe_i32 v82, v193, 8, 1
	v_bitop3_b32 v149, v86, s74, v82 bitop3:0xe4
	v_bfe_i32 v82, v193, 9, 1
	v_bitop3_b32 v150, v87, s74, v82 bitop3:0xe4
	v_bfe_i32 v82, v193, 10, 1
	v_bitop3_b32 v88, v88, s74, v82 bitop3:0xe4
	v_bfe_i32 v82, v193, 11, 1
	v_bitop3_b32 v89, v89, s74, v82 bitop3:0xe4
	v_bfe_i32 v82, v193, 16, 1
	v_bitop3_b32 v90, v90, s74, v82 bitop3:0xe4
	v_bfe_i32 v82, v193, 17, 1
	v_bitop3_b32 v91, v91, s74, v82 bitop3:0xe4
	v_bfe_i32 v82, v193, 18, 1
	v_bitop3_b32 v92, v92, s74, v82 bitop3:0xe4
	v_bfe_i32 v82, v193, 19, 1
	v_bitop3_b32 v93, v93, s74, v82 bitop3:0xe4
	v_bfe_i32 v82, v193, 24, 1
	v_bitop3_b32 v94, v94, s74, v82 bitop3:0xe4
	v_bfe_i32 v82, v193, 25, 1
	v_bitop3_b32 v95, v95, s74, v82 bitop3:0xe4
	v_bfe_i32 v82, v193, 26, 1
	v_bitop3_b32 v96, v96, s74, v82 bitop3:0xe4
	v_bfe_i32 v82, v193, 27, 1
	v_bitop3_b32 v97, v97, s74, v82 bitop3:0xe4
	v_max_f32_e32 v82, v192, v146
	v_max3_f32 v82, v82, v147, v148
	v_max3_f32 v82, v82, v149, v150
	v_max3_f32 v82, v82, v88, v89
	v_max3_f32 v82, v82, v90, v91
	v_lshrrev_b32_e32 v194, v163, v229
	v_max3_f32 v82, v82, v92, v93
	v_bfe_i32 v195, v194, 0, 1
	v_bfe_i32 v172, v194, 1, 1
	v_max3_f32 v82, v82, v94, v95
	v_bitop3_b32 v66, v66, s74, v195 bitop3:0xe4
	v_bfe_i32 v83, v194, 2, 1
	v_bfe_i32 v84, v194, 3, 1
	v_max3_f32 v230, v82, v96, v97
	v_bitop3_b32 v67, v67, s74, v172 bitop3:0xe4
	v_bfe_i32 v85, v194, 8, 1
	v_bfe_i32 v86, v194, 9, 1
	v_bitop3_b32 v82, v68, s74, v83 bitop3:0xe4
	v_max3_f32 v68, v230, v66, v67
	v_bitop3_b32 v83, v69, s74, v84 bitop3:0xe4
	v_bfe_i32 v87, v194, 10, 1
	v_bfe_i32 v151, v194, 11, 1
	v_bitop3_b32 v84, v70, s74, v85 bitop3:0xe4
	v_max3_f32 v68, v68, v82, v83
	v_bitop3_b32 v85, v71, s74, v86 bitop3:0xe4
	v_bfe_i32 v152, v194, 16, 1
	v_bfe_i32 v153, v194, 17, 1
	v_bitop3_b32 v86, v72, s74, v87 bitop3:0xe4
	v_max3_f32 v68, v68, v84, v85
	v_bitop3_b32 v87, v73, s74, v151 bitop3:0xe4
	v_bfe_i32 v154, v194, 18, 1
	v_bfe_i32 v155, v194, 19, 1
	v_bitop3_b32 v74, v74, s74, v152 bitop3:0xe4
	v_max3_f32 v69, v68, v86, v87
	v_bitop3_b32 v75, v75, s74, v153 bitop3:0xe4
	v_bfe_i32 v156, v194, 24, 1
	v_bfe_i32 v157, v194, 25, 1
	v_bitop3_b32 v68, v76, s74, v154 bitop3:0xe4
	v_max3_f32 v71, v69, v74, v75
	v_bitop3_b32 v69, v77, s74, v155 bitop3:0xe4
	v_bfe_i32 v230, v194, 26, 1
	v_bfe_i32 v231, v194, 27, 1
	v_bitop3_b32 v70, v78, s74, v156 bitop3:0xe4
	v_max3_f32 v73, v71, v68, v69
	v_bitop3_b32 v71, v79, s74, v157 bitop3:0xe4
	v_bitop3_b32 v72, v80, s74, v230 bitop3:0xe4
	v_max3_f32 v76, v73, v70, v71
	v_bitop3_b32 v73, v81, s74, v231 bitop3:0xe4
	v_max3_f32 v76, v76, v72, v73
	v_mov_b32_e32 v77, v76
	s_nop 1
	v_permlane32_swap_b32_e32 v76, v77
	v_max_f32_e32 v76, v76, v77
	v_sub_f32_e32 v77, v76, v206
	v_mul_f32_e32 v77, 0x3db504f3, v77
	v_cmp_ge_f32_e32 vcc, s75, v77
	s_cmp_eq_u64 vcc, exec
	s_cselect_b64 s[6:7], -1, 0
